# attention: priorities QK=1 / softmax head=0 / P.V MFMA part=2 in both halves, K/V tile DMA issued behind the first K fragment reads of the QK segment
# speedup vs baseline: 1.0077x; 1.0002x over previous
; #define LAS __attribute__((address_space(3)))
; __device__ __forceinline__ void attn_issue_v(const Frame& F, const unsigned char* vtile, LAS unsigned char* buf) {
;     unsigned lo = F.lane * 16; asm volatile("" : "+v"(lo));
; #pragma unroll
;     for (int j = 0; j < 2; ++j) __builtin_amdgcn_global_load_lds((const unsigned*)(vtile + (size_t)(F.wave * 2 + j) * 1024 + lo), (LAS unsigned*)(buf + (F.wave * 2 + j) * 1024), 16, 0, 0);
; }
.LBB0_1013:
	s_lshl_b32 s89, s89, 14
	s_add_u32 s92, s42, s89
	s_addc_u32 s93, s43, 0
	s_lshl_b32 s89, s75, 14
	s_waitcnt vmcnt(8)
	s_add_i32 s89, s89, 0
	v_mov_b32_e32 v2, v164
	s_waitcnt lgkmcnt(0)
	s_barrier
	s_setprio 1
	s_add_i32 s89, s89, 0x12000
	s_add_i32 vcc_lo, s89, s59
	s_add_i32 vcc_hi, s89, s60
	s_add_u32 s98, s92, s14
	s_addc_u32 s99, s93, s15
	s_add_u32 s100, s92, s16
	s_addc_u32 s101, s93, s17
	s_cmp_gt_i32 s90, s70
	s_cbranch_scc1 .Lmy_attn_skipqk_b
	s_mul_i32 s89, s0, 0x6000
	v_add_u32_e32 v2, s89, v174
	v_add_u32_e32 v16, s89, v175
	ds_read_b128 v[4:7], v2
	ds_read_b128 v[8:11], v2 offset:12288
	ds_read_b128 v[12:15], v16
	ds_read_b128 v[186:189], v16 offset:12288
	v_add_u32_e32 v17, s89, v176
	v_add_u32_e32 v185, s89, v177
	ds_read_b128 v[190:193], v17
	ds_read_b128 v[194:197], v17 offset:12288
	ds_read_b128 v[198:201], v185
	ds_read_b128 v[202:205], v185 offset:12288
	ds_read_b128 v[206:209], v2 offset:128
	ds_read_b128 v[210:213], v2 offset:12416
	ds_read_b128 v[214:217], v16 offset:128
	ds_read_b128 v[218:221], v16 offset:12416
	s_mov_b32 m0, vcc_lo
	s_nop 0
	global_load_lds_dwordx4 v164, s[98:99]
	s_mov_b32 m0, vcc_hi
	s_nop 0
	global_load_lds_dwordx4 v164, s[100:101]
	s_waitcnt lgkmcnt(8)
	v_mfma_f32_32x32x16_bf16 v[98:113], v[4:7], v[114:117], 0
	v_mfma_f32_32x32x16_bf16 v[98:113], v[12:15], v[118:121], v[98:113]
	v_mfma_f32_32x32x16_bf16 v[82:97], v[8:11], v[114:117], 0
	v_mfma_f32_32x32x16_bf16 v[82:97], v[186:189], v[118:121], v[82:97]
	ds_read_b128 v[4:7], v17 offset:128
	ds_read_b128 v[8:11], v17 offset:12416
	ds_read_b128 v[12:15], v185 offset:128
	ds_read_b128 v[186:189], v185 offset:12416
	s_waitcnt lgkmcnt(8)
	v_mfma_f32_32x32x16_bf16 v[98:113], v[190:193], v[122:125], v[98:113]
	v_mfma_f32_32x32x16_bf16 v[98:113], v[198:201], v[126:129], v[98:113]
	v_mfma_f32_32x32x16_bf16 v[82:97], v[194:197], v[122:125], v[82:97]
	v_mfma_f32_32x32x16_bf16 v[82:97], v[202:205], v[126:129], v[82:97]
	ds_read_b128 v[190:193], v2 offset:256
	ds_read_b128 v[194:197], v2 offset:12544
	ds_read_b128 v[198:201], v16 offset:256
	ds_read_b128 v[202:205], v16 offset:12544
	s_waitcnt lgkmcnt(8)
	v_mfma_f32_32x32x16_bf16 v[98:113], v[206:209], v[130:133], v[98:113]
	v_mfma_f32_32x32x16_bf16 v[98:113], v[214:217], v[134:137], v[98:113]
	v_mfma_f32_32x32x16_bf16 v[82:97], v[210:213], v[130:133], v[82:97]
	v_mfma_f32_32x32x16_bf16 v[82:97], v[218:221], v[134:137], v[82:97]
	ds_read_b128 v[206:209], v17 offset:256
	ds_read_b128 v[210:213], v17 offset:12544
	ds_read_b128 v[214:217], v185 offset:256
	ds_read_b128 v[218:221], v185 offset:12544
	s_waitcnt lgkmcnt(8)
	v_mfma_f32_32x32x16_bf16 v[98:113], v[4:7], v[138:141], v[98:113]
	v_mfma_f32_32x32x16_bf16 v[98:113], v[12:15], v[142:145], v[98:113]
	v_mfma_f32_32x32x16_bf16 v[82:97], v[8:11], v[138:141], v[82:97]
	v_mfma_f32_32x32x16_bf16 v[82:97], v[186:189], v[142:145], v[82:97]
	s_waitcnt lgkmcnt(4)
	v_mfma_f32_32x32x16_bf16 v[98:113], v[190:193], v[146:149], v[98:113]
	v_mfma_f32_32x32x16_bf16 v[98:113], v[198:201], v[154:157], v[98:113]
	v_mfma_f32_32x32x16_bf16 v[82:97], v[194:197], v[146:149], v[82:97]
	v_mfma_f32_32x32x16_bf16 v[82:97], v[202:205], v[154:157], v[82:97]
	s_waitcnt lgkmcnt(0)
	v_mfma_f32_32x32x16_bf16 v[98:113], v[206:209], v[150:153], v[98:113]
	v_mfma_f32_32x32x16_bf16 v[98:113], v[214:217], v[158:161], v[98:113]
	v_mfma_f32_32x32x16_bf16 v[82:97], v[210:213], v[150:153], v[82:97]
	v_mfma_f32_32x32x16_bf16 v[82:97], v[218:221], v[158:161], v[82:97]
	s_branch .LBB0_1016

.LBB0_1025:
	s_lshl_b32 s0, s73, 14
	s_add_i32 s0, s0, 0x12000
	v_add_u32_e32 v2, s0, v163
	ds_read_b128 v[222:225], v2
	ds_read_b128 v[226:229], v2 offset:4096
	ds_read_b128 v[230:233], v2 offset:8192
	ds_read_b128 v[234:237], v2 offset:12288
	v_add_u32_e32 v2, s0, v171
	ds_read_b128 v[238:241], v2
	ds_read_b128 v[242:245], v2 offset:4096
	ds_read_b128 v[246:249], v2 offset:8192
	ds_read_b128 v[250:253], v2 offset:12288
	v_exp_f32_e32 v2, v98
	v_exp_f32_e32 v4, v99
	v_exp_f32_e32 v5, v100
	v_exp_f32_e32 v6, v101
	v_add_f32_e32 v7, 0, v2
	v_exp_f32_e32 v8, v102
	v_add_f32_e32 v7, v4, v7
	v_exp_f32_e32 v9, v103
	v_add_f32_e32 v7, v5, v7
	v_exp_f32_e32 v10, v104
	v_add_f32_e32 v7, v6, v7
	v_exp_f32_e32 v11, v105
	v_add_f32_e32 v7, v8, v7
	v_exp_f32_e32 v16, v106
	v_add_f32_e32 v7, v9, v7
	v_exp_f32_e32 v106, v107
	v_add_f32_e32 v7, v10, v7
	v_exp_f32_e32 v107, v108
	v_add_f32_e32 v7, v11, v7
	v_exp_f32_e32 v108, v109
	v_add_f32_e32 v7, v16, v7
	v_exp_f32_e32 v109, v110
	v_add_f32_e32 v7, v106, v7
	v_exp_f32_e32 v110, v111
	v_add_f32_e32 v7, v107, v7
	v_exp_f32_e32 v111, v112
	v_add_f32_e32 v7, v108, v7
	v_exp_f32_e32 v112, v113
	v_add_f32_e32 v7, v109, v7
	v_add_f32_e32 v7, v110, v7
	v_add_f32_e32 v7, v111, v7
	v_cvt_pk_bf16_f32 v4, v2, v4
	v_add_f32_e32 v17, v112, v7
	v_cvt_pk_bf16_f32 v5, v5, v6
	v_cvt_pk_bf16_f32 v6, v8, v9
	v_cvt_pk_bf16_f32 v7, v10, v11
	v_cvt_pk_bf16_f32 v106, v16, v106
	v_cvt_pk_bf16_f32 v107, v107, v108
	v_cvt_pk_bf16_f32 v108, v109, v110
	v_cvt_pk_bf16_f32 v109, v111, v112
	s_setprio 2
	s_waitcnt lgkmcnt(7)
	v_mfma_f32_32x32x16_bf16 v[66:81], v[222:225], v[4:7], v[66:81]
	v_exp_f32_e32 v2, v82
	v_exp_f32_e32 v179, v83
	s_nop 0
	v_add_f32_e32 v193, v2, v179
	s_waitcnt lgkmcnt(6)
	v_mfma_f32_32x32x16_bf16 v[50:65], v[226:229], v[4:7], v[50:65]
	v_exp_f32_e32 v192, v84
	v_exp_f32_e32 v16, v85
	s_nop 0
	v_add_f32_e32 v8, v192, v16
	v_add_f32_e32 v9, v193, v17
	v_add_f32_e32 v195, v8, v9
	s_waitcnt lgkmcnt(5)
	v_mfma_f32_32x32x16_bf16 v[34:49], v[230:233], v[4:7], v[34:49]
	v_exp_f32_e32 v17, v86
	v_exp_f32_e32 v193, v87
	s_nop 0
	v_add_f32_e32 v197, v17, v193
	s_waitcnt lgkmcnt(4)
	v_mfma_f32_32x32x16_bf16 v[18:33], v[234:237], v[4:7], v[18:33]
	v_exp_f32_e32 v196, v88
	v_exp_f32_e32 v194, v89
	s_nop 0
	v_add_f32_e32 v8, v196, v194
	v_add_f32_e32 v9, v197, v195
	v_add_f32_e32 v199, v8, v9
	v_add_u32_e32 v82, s0, v172
	ds_read_b128 v[4:7], v82
	ds_read_b128 v[8:11], v82 offset:4096
	ds_read_b128 v[12:15], v82 offset:8192
	ds_read_b128 v[82:85], v82 offset:12288
	s_waitcnt lgkmcnt(7)
	v_mfma_f32_32x32x16_bf16 v[66:81], v[238:241], v[106:109], v[66:81]
	v_exp_f32_e32 v195, v90
	v_exp_f32_e32 v197, v91
	s_nop 0
	v_add_f32_e32 v201, v195, v197
	s_waitcnt lgkmcnt(6)
	v_mfma_f32_32x32x16_bf16 v[50:65], v[242:245], v[106:109], v[50:65]
	v_exp_f32_e32 v200, v92
	v_exp_f32_e32 v198, v93
	s_nop 0
	v_add_f32_e32 v86, v200, v198
	v_add_f32_e32 v87, v201, v199
	v_add_f32_e32 v111, v86, v87
	s_waitcnt lgkmcnt(5)
	v_mfma_f32_32x32x16_bf16 v[34:49], v[246:249], v[106:109], v[34:49]
	v_exp_f32_e32 v180, v94
	v_exp_f32_e32 v181, v95
	s_nop 0
	v_add_f32_e32 v113, v180, v181
	s_waitcnt lgkmcnt(4)
	v_mfma_f32_32x32x16_bf16 v[18:33], v[250:253], v[106:109], v[18:33]
	v_exp_f32_e32 v112, v96
	v_exp_f32_e32 v110, v97
	s_nop 0
	v_add_f32_e32 v86, v112, v110
	v_add_f32_e32 v87, v113, v111
	v_add_f32_e32 v102, v86, v87
	v_add_u32_e32 v98, s0, v173
	ds_read_b128 v[86:89], v98
	ds_read_b128 v[90:93], v98 offset:4096
	ds_read_b128 v[94:97], v98 offset:8192
	ds_read_b128 v[98:101], v98 offset:12288
	v_add_f32_e32 v178, v178, v102
	v_cvt_pk_bf16_f32 v102, v2, v179
	v_cvt_pk_bf16_f32 v103, v192, v16
	v_cvt_pk_bf16_f32 v104, v17, v193
	v_cvt_pk_bf16_f32 v105, v196, v194
	v_cvt_pk_bf16_f32 v106, v195, v197
	v_cvt_pk_bf16_f32 v107, v200, v198
	v_cvt_pk_bf16_f32 v108, v180, v181
	v_cvt_pk_bf16_f32 v109, v112, v110
	s_waitcnt lgkmcnt(7)
	v_mfma_f32_32x32x16_bf16 v[66:81], v[4:7], v[102:105], v[66:81]
	s_waitcnt lgkmcnt(6)
	v_mfma_f32_32x32x16_bf16 v[50:65], v[8:11], v[102:105], v[50:65]
	s_waitcnt lgkmcnt(5)
	v_mfma_f32_32x32x16_bf16 v[34:49], v[12:15], v[102:105], v[34:49]
	s_waitcnt lgkmcnt(4)
	v_mfma_f32_32x32x16_bf16 v[18:33], v[82:85], v[102:105], v[18:33]
	s_waitcnt lgkmcnt(0)
	v_mfma_f32_32x32x16_bf16 v[66:81], v[86:89], v[106:109], v[66:81]
	v_mfma_f32_32x32x16_bf16 v[50:65], v[90:93], v[106:109], v[50:65]
	v_mfma_f32_32x32x16_bf16 v[34:49], v[94:97], v[106:109], v[34:49]
	v_mfma_f32_32x32x16_bf16 v[18:33], v[98:101], v[106:109], v[18:33]

; #define LAS __attribute__((address_space(3)))
; __device__ __forceinline__ void attn_issue_k(const Frame& F, const unsigned char* ktile, LAS unsigned char* buf) {
;     unsigned lo = F.lane * 16; asm volatile("" : "+v"(lo));
; #pragma unroll
;     for (int j = 0; j < 3; ++j) __builtin_amdgcn_global_load_lds((const unsigned*)(ktile + (size_t)(F.wave * 3 + j) * 1024 + lo), (LAS unsigned*)(buf + (F.wave * 3 + j) * 1024), 16, 0, 0);
; }
.LBB0_1027:
	s_setprio 1
	s_min_u32 s75, s33, s45
	s_mul_i32 s0, s75, 0x6000
	s_add_u32 s0, s40, s0
	s_addc_u32 s1, s41, 0
	s_mul_i32 s88, s74, 0x6000
	v_mov_b32_e32 v2, v164
	s_add_i32 s88, s88, 0
	s_mov_b32 s98, s0
	s_mov_b32 s99, s1
	s_mov_b32 vcc_lo, s88
	s_cmp_le_u32 s72, s70
	s_cselect_b64 s[0:1], -1, 0
	s_cmp_gt_u32 s72, s70
	s_cbranch_scc1 .Lmy_attn_skipqk_a
	s_mul_i32 s88, s73, 0x6000
	v_add_u32_e32 v2, s88, v174
	v_add_u32_e32 v16, s88, v175
	ds_read_b128 v[4:7], v2
	ds_read_b128 v[8:11], v2 offset:12288
	ds_read_b128 v[12:15], v16
	ds_read_b128 v[180:183], v16 offset:12288
	v_add_u32_e32 v17, s88, v176
	v_add_u32_e32 v179, s88, v177
	ds_read_b128 v[184:187], v17
	ds_read_b128 v[188:191], v17 offset:12288
	ds_read_b128 v[192:195], v179
	ds_read_b128 v[196:199], v179 offset:12288
	ds_read_b128 v[200:203], v2 offset:128
	ds_read_b128 v[204:207], v2 offset:12416
	ds_read_b128 v[208:211], v16 offset:128
	ds_read_b128 v[212:215], v16 offset:12416
	s_add_i32 m0, vcc_lo, s56
	s_add_u32 s100, s98, s8
	s_addc_u32 s101, s99, s9
	global_load_lds_dwordx4 v164, s[100:101]
	s_add_i32 m0, vcc_lo, s57
	s_add_u32 s100, s98, s10
	s_addc_u32 s101, s99, s11
	global_load_lds_dwordx4 v164, s[100:101]
	s_add_i32 m0, vcc_lo, s58
	s_add_u32 s100, s98, s12
	s_addc_u32 s101, s99, s13
	global_load_lds_dwordx4 v164, s[100:101]
	s_waitcnt lgkmcnt(8)
	v_mfma_f32_32x32x16_bf16 v[98:113], v[4:7], v[114:117], 0
	v_mfma_f32_32x32x16_bf16 v[98:113], v[12:15], v[118:121], v[98:113]
	v_mfma_f32_32x32x16_bf16 v[82:97], v[8:11], v[114:117], 0
	v_mfma_f32_32x32x16_bf16 v[82:97], v[180:183], v[118:121], v[82:97]
	ds_read_b128 v[4:7], v17 offset:128
	ds_read_b128 v[8:11], v17 offset:12416
	ds_read_b128 v[12:15], v179 offset:128
	ds_read_b128 v[180:183], v179 offset:12416
	s_waitcnt lgkmcnt(8)
	v_mfma_f32_32x32x16_bf16 v[98:113], v[184:187], v[122:125], v[98:113]
	v_mfma_f32_32x32x16_bf16 v[98:113], v[192:195], v[126:129], v[98:113]
	v_mfma_f32_32x32x16_bf16 v[82:97], v[188:191], v[122:125], v[82:97]
	v_mfma_f32_32x32x16_bf16 v[82:97], v[196:199], v[126:129], v[82:97]
	ds_read_b128 v[184:187], v2 offset:256
	ds_read_b128 v[188:191], v2 offset:12544
	ds_read_b128 v[192:195], v16 offset:256
	ds_read_b128 v[196:199], v16 offset:12544
	s_waitcnt lgkmcnt(8)
	v_mfma_f32_32x32x16_bf16 v[98:113], v[200:203], v[130:133], v[98:113]
	v_mfma_f32_32x32x16_bf16 v[98:113], v[208:211], v[134:137], v[98:113]
	v_mfma_f32_32x32x16_bf16 v[82:97], v[204:207], v[130:133], v[82:97]
	v_mfma_f32_32x32x16_bf16 v[82:97], v[212:215], v[134:137], v[82:97]
	ds_read_b128 v[200:203], v17 offset:256
	ds_read_b128 v[204:207], v17 offset:12544
	ds_read_b128 v[208:211], v179 offset:256
	ds_read_b128 v[212:215], v179 offset:12544
	s_waitcnt lgkmcnt(8)
	v_mfma_f32_32x32x16_bf16 v[98:113], v[4:7], v[138:141], v[98:113]
	v_mfma_f32_32x32x16_bf16 v[98:113], v[12:15], v[142:145], v[98:113]
	v_mfma_f32_32x32x16_bf16 v[82:97], v[8:11], v[138:141], v[82:97]
	v_mfma_f32_32x32x16_bf16 v[82:97], v[180:183], v[142:145], v[82:97]
	s_waitcnt lgkmcnt(4)
	v_mfma_f32_32x32x16_bf16 v[98:113], v[184:187], v[146:149], v[98:113]
	v_mfma_f32_32x32x16_bf16 v[98:113], v[192:195], v[154:157], v[98:113]
	v_mfma_f32_32x32x16_bf16 v[82:97], v[188:191], v[146:149], v[82:97]
	v_mfma_f32_32x32x16_bf16 v[82:97], v[196:199], v[154:157], v[82:97]
	s_waitcnt lgkmcnt(0)
	v_mfma_f32_32x32x16_bf16 v[98:113], v[200:203], v[150:153], v[98:113]
	v_mfma_f32_32x32x16_bf16 v[98:113], v[208:211], v[158:161], v[98:113]
	v_mfma_f32_32x32x16_bf16 v[82:97], v[204:207], v[150:153], v[82:97]
	v_mfma_f32_32x32x16_bf16 v[82:97], v[212:215], v[158:161], v[82:97]
	s_branch .LBB0_1030
